# mLSTM next-chunk scans by DPP row shifts instead of LDS bpermute chains; DSA output stores widened to 16 bytes
# speedup vs baseline: 1.0079x; 1.0079x over previous
; #define LAS __attribute__((address_space(3)))
; __device__ __forceinline__ unsigned pk2(float lo, float hi) { f32x2_t v = {lo, hi}; bf16x2_t b = __builtin_convertvector(v, bf16x2_t); return __builtin_bit_cast(unsigned, b); }
; __device__ __forceinline__ f32x4 mfma16(bf16x8 a, bf16x8 b, f32x4 c) { return __builtin_amdgcn_mfma_f32_16x16x32_bf16(a, b, c, 0, 0, 0); }
; __device__ __forceinline__ void mlstm_unit(const Args& a, LAS unsigned char* lds, int b, int h, int tid_in, int wave, int lane_in) {
;     ...
;         {
;             const float dec = __expf(mstate - M63);
; #pragma unroll
;             for (int et = 0; et < 9; ++et) {
;                 if ((et & 1) == 0) asm volatile("" ::: "memory");
;                 Creg[et] = Creg[et] * dec;
; #pragma unroll
;                 for (int kk = 0; kk < 2; ++kk) Creg[et] = mfma16(*(const LAS bf16x8*)(vT + (16 * et + fr) * TS + 8 * ((4 * kk + fq) ^ (et & 7))), *(const LAS bf16x8*)(kTw + (16 * wave + fr) * TS + 8 * ((4 * kk + fq) ^ (wave & 7))), Creg[et]);
;                 { const unsigned w0 = pk2(Creg[et][0], Creg[et][1]), w1 = pk2(Creg[et][2], Creg[et][3]); const int e0 = 16 * et + 4 * fq, dcol = 16 * wave + fr;
;                   C_s[(e0 + 0) * QS + dcol] = (bf16)(w0 & 0xffffu); C_s[(e0 + 1) * QS + dcol] = (bf16)(w0 >> 16); C_s[(e0 + 2) * QS + dcol] = (bf16)(w1 & 0xffffu); C_s[(e0 + 3) * QS + dcol] = (bf16)(w1 >> 16); }
;             }
;         }
.LBB0_1069:
	v_readlane_b32 s4, v254, 9
	v_mad_u32_u24 v106, v137, s79, 0
	s_nop 2
	v_subrev_f32_e32 v88, s50, v166
	v_or_b32_e32 v89, s4, v137
	v_mul_lo_u32 v90, v89, s79
	v_add_u32_e32 v102, 0, v90
	v_add_u32_e32 v90, v106, v136
	ds_read_b128 v[90:93], v90 offset:53248
	v_xor_b32_e32 v94, s39, v168
	v_mul_f32_e32 v88, 0x3fb8aa3b, v88
	v_lshl_add_u32 v107, v94, 4, v102
	v_exp_f32_e32 v88, v88
	ds_read_b128 v[94:97], v107 offset:34816
	v_lshlrev_b32_e32 v108, 4, v116
	v_add_u32_e32 v98, v106, v108
	ds_read_b128 v[98:101], v98 offset:53248
	v_pk_mul_f32 v[50:51], v[50:51], v[88:89] op_sel_hi:[1,0]
	v_pk_mul_f32 v[48:49], v[48:49], v[88:89] op_sel_hi:[1,0]
	s_movk_i32 s4, 0x440
	v_mul_lo_u32 v110, v168, s4
	s_waitcnt lgkmcnt(1)
	v_mfma_f32_16x16x32_bf16 v[48:51], v[90:93], v[94:97], v[48:51]
	v_xor_b32_e32 v90, s39, v116
	v_lshl_add_u32 v109, v90, 4, v102
	ds_read_b128 v[90:93], v109 offset:34816
	s_waitcnt lgkmcnt(0)
	v_mfma_f32_16x16x32_bf16 v[48:51], v[98:101], v[90:93], v[48:51]
	v_lshlrev_b32_e32 v89, 1, v89
	v_add3_u32 v92, s58, v110, v89
	v_xad_u32 v98, v108, 16, v106
	s_nop 4
	v_cvt_pk_bf16_f32 v90, v48, v49
	v_cvt_pk_bf16_f32 v91, v50, v51
	ds_write_b16 v92, v90
	ds_write_b16_d16_hi v92, v90 offset:272
	ds_write_b16 v92, v91 offset:544
	ds_write_b16_d16_hi v92, v91 offset:816
	v_xad_u32 v90, v136, 16, v106
	ds_read_b128 v[90:93], v90 offset:55552
	ds_read_b128 v[94:97], v107 offset:34816
	ds_read_b128 v[98:101], v98 offset:55552
	ds_read_b128 v[102:105], v109 offset:34816
	v_pk_mul_f32 v[46:47], v[46:47], v[88:89] op_sel_hi:[1,0]
	v_pk_mul_f32 v[44:45], v[44:45], v[88:89] op_sel_hi:[1,0]
	v_pk_mul_f32 v[54:55], v[54:55], v[88:89] op_sel_hi:[1,0]
	v_pk_mul_f32 v[52:53], v[52:53], v[88:89] op_sel_hi:[1,0]
	s_waitcnt lgkmcnt(2)
	v_mfma_f32_16x16x32_bf16 v[44:47], v[90:93], v[94:97], v[44:47]
	v_add3_u32 v92, s85, v110, v89
	v_pk_mul_f32 v[58:59], v[58:59], v[88:89] op_sel_hi:[1,0]
	v_pk_mul_f32 v[56:57], v[56:57], v[88:89] op_sel_hi:[1,0]
	s_waitcnt lgkmcnt(0)
	v_mfma_f32_16x16x32_bf16 v[44:47], v[98:101], v[102:105], v[44:47]
	v_xad_u32 v98, v108, 32, v106
	v_pk_mul_f32 v[62:63], v[62:63], v[88:89] op_sel_hi:[1,0]
	v_pk_mul_f32 v[60:61], v[60:61], v[88:89] op_sel_hi:[1,0]
	v_pk_mul_f32 v[66:67], v[66:67], v[88:89] op_sel_hi:[1,0]
	v_pk_mul_f32 v[64:65], v[64:65], v[88:89] op_sel_hi:[1,0]
	s_nop 2
	v_cvt_pk_bf16_f32 v90, v44, v45
	v_cvt_pk_bf16_f32 v91, v46, v47
	ds_write_b16 v92, v90
	ds_write_b16_d16_hi v92, v90 offset:272
	ds_write_b16 v92, v91 offset:544
	ds_write_b16_d16_hi v92, v91 offset:816
	v_xad_u32 v90, v136, 32, v106
	ds_read_b128 v[90:93], v90 offset:57856
	ds_read_b128 v[94:97], v107 offset:34816
	ds_read_b128 v[98:101], v98 offset:57856
	ds_read_b128 v[102:105], v109 offset:34816
	s_waitcnt lgkmcnt(2)
	v_mfma_f32_16x16x32_bf16 v[52:55], v[90:93], v[94:97], v[52:55]
	v_add3_u32 v92, s86, v110, v89
	v_pk_mul_f32 v[70:71], v[70:71], v[88:89] op_sel_hi:[1,0]
	v_pk_mul_f32 v[68:69], v[68:69], v[88:89] op_sel_hi:[1,0]
	s_waitcnt lgkmcnt(0)
	v_mfma_f32_16x16x32_bf16 v[52:55], v[98:101], v[102:105], v[52:55]
	v_xad_u32 v98, v108, 48, v106
	v_pk_mul_f32 v[78:79], v[78:79], v[88:89] op_sel_hi:[1,0]
	v_pk_mul_f32 v[76:77], v[76:77], v[88:89] op_sel_hi:[1,0]
	v_pk_mul_f32 v[74:75], v[74:75], v[88:89] op_sel_hi:[1,0]
	s_nop 3
	v_cvt_pk_bf16_f32 v90, v52, v53
	v_cvt_pk_bf16_f32 v91, v54, v55
	ds_write_b16 v92, v90
	ds_write_b16_d16_hi v92, v90 offset:272
	ds_write_b16 v92, v91 offset:544
	ds_write_b16_d16_hi v92, v91 offset:816
	v_xad_u32 v90, v136, 48, v106
	ds_read_b128 v[90:93], v90 offset:60160
	ds_read_b128 v[94:97], v107 offset:34816
	ds_read_b128 v[98:101], v98 offset:60160
	ds_read_b128 v[102:105], v109 offset:34816
	s_waitcnt lgkmcnt(2)
	v_mfma_f32_16x16x32_bf16 v[56:59], v[90:93], v[94:97], v[56:59]
	v_add3_u32 v92, s87, v110, v89
	v_pk_mul_f32 v[72:73], v[72:73], v[88:89] op_sel_hi:[1,0]
	v_ashrrev_i32_e32 v88, 3, v167
	s_waitcnt lgkmcnt(0)
	v_mfma_f32_16x16x32_bf16 v[56:59], v[98:101], v[102:105], v[56:59]
	v_xad_u32 v98, v108, 64, v106
	v_add_u32_e32 v88, s34, v88
	s_waitcnt vmcnt(0)
	v_lshlrev_b32_e32 v122, 16, v85
	v_and_b32_e32 v124, 0xffff0000, v85
	s_nop 2
	v_cvt_pk_bf16_f32 v90, v56, v57
	v_cvt_pk_bf16_f32 v91, v58, v59
	ds_write_b16 v92, v90
	ds_write_b16_d16_hi v92, v90 offset:272
	ds_write_b16 v92, v91 offset:544
	ds_write_b16_d16_hi v92, v91 offset:816
	v_xad_u32 v90, v136, 64, v106
	ds_read_b128 v[90:93], v90 offset:62464
	ds_read_b128 v[94:97], v107 offset:34816
	ds_read_b128 v[98:101], v98 offset:62464
	ds_read_b128 v[102:105], v109 offset:34816
	s_waitcnt lgkmcnt(2)
	v_mfma_f32_16x16x32_bf16 v[60:63], v[90:93], v[94:97], v[60:63]
	v_add3_u32 v90, s88, v110, v89
	s_waitcnt lgkmcnt(0)
	v_mfma_f32_16x16x32_bf16 v[60:63], v[98:101], v[102:105], v[60:63]
	v_xad_u32 v98, v108, s89, v106
	s_nop 6
	v_cvt_pk_bf16_f32 v91, v60, v61
	v_cvt_pk_bf16_f32 v92, v62, v63
	ds_write_b16 v90, v91
	ds_write_b16_d16_hi v90, v91 offset:272
	ds_write_b16 v90, v92 offset:544
	ds_write_b16_d16_hi v90, v92 offset:816
	v_xad_u32 v90, v136, s89, v106
	ds_read_b128 v[90:93], v90 offset:64768
	ds_read_b128 v[94:97], v107 offset:34816
	ds_read_b128 v[98:101], v98 offset:64768
	ds_read_b128 v[102:105], v109 offset:34816
	s_waitcnt lgkmcnt(2)
	v_mfma_f32_16x16x32_bf16 v[64:67], v[90:93], v[94:97], v[64:67]
	v_add3_u32 v90, s90, v110, v89
	v_add_u32_e32 v106, 0xd000, v106
	s_waitcnt lgkmcnt(0)
; #define LAS __attribute__((address_space(3)))
; __device__ __forceinline__ unsigned pk2(float lo, float hi) { f32x2_t v = {lo, hi}; bf16x2_t b = __builtin_convertvector(v, bf16x2_t); return __builtin_bit_cast(unsigned, b); }
; __device__ __forceinline__ f32x4 mfma16(bf16x8 a, bf16x8 b, f32x4 c) { return __builtin_amdgcn_mfma_f32_16x16x32_bf16(a, b, c, 0, 0, 0); }
; #define LDS_BARRIER() do { asm volatile("s_waitcnt lgkmcnt(0)" ::: "memory"); __builtin_amdgcn_s_barrier(); asm volatile("" ::: "memory"); } while (0)
; __device__ __forceinline__ void mlstm_unit(const Args& a, LAS unsigned char* lds, int b, int h, int tid_in, int wave, int lane_in) {
;     ...
;             for (int et = 0; et < 9; ++et) {
;                 if ((et & 1) == 0) asm volatile("" ::: "memory");
;                 Creg[et] = Creg[et] * dec;
; #pragma unroll
;                 for (int kk = 0; kk < 2; ++kk) Creg[et] = mfma16(*(const LAS bf16x8*)(vT + (16 * et + fr) * TS + 8 * ((4 * kk + fq) ^ (et & 7))), *(const LAS bf16x8*)(kTw + (16 * wave + fr) * TS + 8 * ((4 * kk + fq) ^ (wave & 7))), Creg[et]);
;                 { const unsigned w0 = pk2(Creg[et][0], Creg[et][1]), w1 = pk2(Creg[et][2], Creg[et][3]); const int e0 = 16 * et + 4 * fq, dcol = 16 * wave + fr;
;                   C_s[(e0 + 0) * QS + dcol] = (bf16)(w0 & 0xffffu); C_s[(e0 + 1) * QS + dcol] = (bf16)(w0 >> 16); C_s[(e0 + 2) * QS + dcol] = (bf16)(w1 & 0xffffu); C_s[(e0 + 3) * QS + dcol] = (bf16)(w1 >> 16); }
;             }
;         }
;         LDS_BARRIER();
;         {
;             const int jr = lane >> 3, ec = lane & 7, j = 8 * wave + jr;
;             f32x4 nv[4], gv[4];
; #pragma unroll
;             for (int k = 0; k < 4; ++k) { nv[k] = *(const LAS f32x4*)(numS + j * NS + 16 * ec + 4 * k); gv[k] = *(const LAS f32x4*)(hg_s + 16 * ec + 4 * k); }
;             const float den = numS[j * NS + 128];
;             const float dn = fmaxf(fabsf(den), __expf(-(gate[par * 192 + 64 + j] + gate[par * 192 + j])));
;             const float idn = __builtin_amdgcn_rcpf(dn); float ss = 0.f;
; #pragma unroll
;             for (int k = 0; k < 4; ++k) { nv[k] = nv[k] * idn; ss += (nv[k][0] * nv[k][0] + nv[k][1] * nv[k][1]) + (nv[k][2] * nv[k][2] + nv[k][3] * nv[k][3]); }
;             ss += __shfl_xor(ss, 1); ss += __shfl_xor(ss, 2); ss += __shfl_xor(ss, 4);
	v_mfma_f32_16x16x32_bf16 v[64:67], v[98:101], v[102:105], v[64:67]
	v_xad_u32 v98, v108, s91, v106
	s_nop 6
	v_cvt_pk_bf16_f32 v91, v64, v65
	v_cvt_pk_bf16_f32 v92, v66, v67
	ds_write_b16 v90, v91
	ds_write_b16_d16_hi v90, v91 offset:272
	ds_write_b16 v90, v92 offset:544
	ds_write_b16_d16_hi v90, v92 offset:816
	v_xad_u32 v90, v136, s91, v106
	ds_read_b128 v[90:93], v90 offset:13824
	ds_read_b128 v[94:97], v107 offset:34816
	ds_read_b128 v[98:101], v98 offset:13824
	ds_read_b128 v[102:105], v109 offset:34816
	s_waitcnt lgkmcnt(2)
	v_mfma_f32_16x16x32_bf16 v[68:71], v[90:93], v[94:97], v[68:71]
	v_add3_u32 v90, s92, v110, v89
	s_waitcnt lgkmcnt(0)
	v_mfma_f32_16x16x32_bf16 v[68:71], v[98:101], v[102:105], v[68:71]
	v_xad_u32 v98, v108, s74, v106
	s_nop 6
	v_cvt_pk_bf16_f32 v91, v68, v69
	v_cvt_pk_bf16_f32 v92, v70, v71
	ds_write_b16 v90, v91
	ds_write_b16_d16_hi v90, v91 offset:272
	ds_write_b16 v90, v92 offset:544
	ds_write_b16_d16_hi v90, v92 offset:816
	v_xad_u32 v90, v136, s74, v106
	ds_read_b128 v[90:93], v90 offset:16128
	ds_read_b128 v[94:97], v107 offset:34816
	ds_read_b128 v[98:101], v98 offset:16128
	ds_read_b128 v[102:105], v109 offset:34816
	s_waitcnt lgkmcnt(2)
	v_mfma_f32_16x16x32_bf16 v[76:79], v[90:93], v[94:97], v[76:79]
	v_add3_u32 v90, s93, v110, v89
	v_add_u32_e32 v91, v106, v136
	v_add3_u32 v89, s94, v110, v89
	s_waitcnt lgkmcnt(0)
	v_mfma_f32_16x16x32_bf16 v[76:79], v[98:101], v[102:105], v[76:79]
	v_add_u32_e32 v98, v106, v108
	s_nop 6
	v_cvt_pk_bf16_f32 v92, v76, v77
	v_cvt_pk_bf16_f32 v93, v78, v79
	ds_write_b16 v90, v92
	ds_write_b16_d16_hi v90, v92 offset:272
	ds_write_b16 v90, v93 offset:544
	ds_write_b16_d16_hi v90, v93 offset:816
	ds_read_b128 v[90:93], v91 offset:18432
	ds_read_b128 v[94:97], v107 offset:34816
	ds_read_b128 v[98:101], v98 offset:18432
	ds_read_b128 v[102:105], v109 offset:34816
	s_waitcnt lgkmcnt(2)
	v_mfma_f32_16x16x32_bf16 v[72:75], v[90:93], v[94:97], v[72:75]
	s_waitcnt lgkmcnt(0)
	v_mfma_f32_16x16x32_bf16 v[72:75], v[98:101], v[102:105], v[72:75]
	s_nop 7
	v_cvt_pk_bf16_f32 v90, v72, v73
	v_cvt_pk_bf16_f32 v91, v74, v75
	ds_write_b16 v89, v90
	ds_write_b16_d16_hi v89, v90 offset:272
	ds_write_b16 v89, v91 offset:544
	ds_write_b16_d16_hi v89, v91 offset:816
	s_waitcnt lgkmcnt(0)
	s_barrier
	v_mul_lo_u32 v89, v88, s84
	v_lshl_add_u32 v88, v88, 2, s13
	ds_read2st64_b32 v[92:93], v88 offset1:1
	v_add_u32_e32 v94, 0, v89
	v_lshlrev_b32_e32 v89, 6, v167
	v_and_b32_e32 v95, 0x1c0, v89
	v_add_u32_e32 v100, v94, v95
	ds_read_b128 v[88:91], v100
	ds_read_b32 v94, v94 offset:512
	s_waitcnt lgkmcnt(2)
	v_add_f32_e32 v92, v93, v92
	v_mul_f32_e32 v92, 0xbfb8aa3b, v92
	v_exp_f32_e32 v92, v92
	v_add_u32_e32 v93, 0, v95
	v_add_u32_e32 v109, 0x1fa00, v93
	s_waitcnt lgkmcnt(0)
	v_max_f32_e64 v93, |v94|, |v94|
	v_max_f32_e32 v92, v93, v92
	v_rcp_f32_e32 v108, v92
	ds_read_b128 v[92:95], v100 offset:16
	ds_read_b128 v[96:99], v100 offset:32
	ds_read_b128 v[100:103], v100 offset:48
	ds_read_b128 v[104:107], v109
	v_pk_mul_f32 v[110:111], v[88:89], v[108:109] op_sel_hi:[1,0]
	v_pk_mul_f32 v[112:113], v[90:91], v[108:109] op_sel_hi:[1,0]
	v_pk_mul_f32 v[90:91], v[110:111], v[110:111]
	v_pk_mul_f32 v[88:89], v[112:113], v[112:113]
	s_waitcnt lgkmcnt(3)
	v_pk_mul_f32 v[116:117], v[94:95], v[108:109] op_sel_hi:[1,0]
	v_pk_mov_b32 v[114:115], v[90:91], v[88:89] op_sel:[1,0]
	v_mov_b32_e32 v91, v89
	v_pk_add_f32 v[88:89], v[114:115], v[90:91]
	v_pk_mul_f32 v[114:115], v[92:93], v[108:109] op_sel_hi:[1,0]
	v_pk_add_f32 v[88:89], v[88:89], v[88:89] op_sel_hi:[0,1]
	v_pk_mul_f32 v[90:91], v[116:117], v[116:117]
	v_pk_mul_f32 v[92:93], v[114:115], v[114:115]
	s_waitcnt lgkmcnt(2)
	v_pk_mul_f32 v[120:121], v[96:97], v[108:109] op_sel_hi:[1,0]
	v_pk_mov_b32 v[94:95], v[92:93], v[90:91] op_sel:[1,0]
	v_mov_b32_e32 v93, v91
	v_pk_mul_f32 v[118:119], v[98:99], v[108:109] op_sel_hi:[1,0]
	v_mul_f32_e32 v88, v120, v120
	v_pk_add_f32 v[90:91], v[94:95], v[92:93]
	v_pk_fma_f32 v[92:93], v[120:121], v[120:121], v[88:89] op_sel_hi:[1,1,0]
	v_mul_f32_e32 v88, v118, v118
	v_pk_add_f32 v[90:91], v[90:91], v[90:91] op_sel_hi:[0,1]
	v_pk_fma_f32 v[94:95], v[118:119], v[118:119], v[88:89] op_sel_hi:[1,1,0]
	s_waitcnt lgkmcnt(1)
	v_pk_mul_f32 v[102:103], v[102:103], v[108:109] op_sel_hi:[1,0]
	v_pk_mul_f32 v[100:101], v[100:101], v[108:109] op_sel_hi:[1,0]
	v_mul_f32_e32 v88, v102, v102
	v_mul_f32_e32 v92, v100, v100
	v_mul_f32_e32 v94, v101, v101
	v_mul_f32_e32 v90, v103, v103
	v_pk_add_f32 v[92:93], v[92:93], v[94:95]
	v_pk_add_f32 v[88:89], v[88:89], v[90:91]
	s_nop 0
	v_pk_add_f32 v[88:89], v[92:93], v[88:89]
	s_nop 0
	v_add_f32_e32 v88, v88, v89
	ds_bpermute_b32 v89, v159, v88
	s_waitcnt lgkmcnt(0)
	v_add_f32_e32 v88, v88, v89
	ds_bpermute_b32 v89, v160, v88
	s_waitcnt lgkmcnt(0)
	v_add_f32_e32 v88, v88, v89
	ds_bpermute_b32 v89, v161, v88
	s_waitcnt lgkmcnt(0)
; #define GAS __attribute__((address_space(1)))
; __device__ __forceinline__ unsigned pk2(float lo, float hi) { f32x2_t v = {lo, hi}; bf16x2_t b = __builtin_convertvector(v, bf16x2_t); return __builtin_bit_cast(unsigned, b); }
; __device__ __forceinline__ float scan_add(float v, int lane) {
; #pragma unroll
;     for (int o = 1; o < 64; o <<= 1) { const float t = __shfl_up(v, o); if (lane >= o) v += t; }
;     return v;
; }
; __device__ __forceinline__ float scan_max(float v, int lane) {
; #pragma unroll
;     for (int o = 1; o < 64; o <<= 1) { const float t = __shfl_up(v, o); if (lane >= o) v = fmaxf(v, t); }
;     return v;
; }
; __device__ __forceinline__ void mlstm_unit(const Args& a, LAS unsigned char* lds, int b, int h, int tid_in, int wave, int lane_in) {
;     ...
;             const float rs = rsqrtf(ss * (1.f / 128.f) + EPS);
;             u32x4 yo[2];
; #pragma unroll
;             for (int k = 0; k < 4; ++k) {
;                 const unsigned w0 = ow2[k >> 1][2 * (k & 1)], w1 = ow2[k >> 1][2 * (k & 1) + 1];
;                 const float o0 = bflo(w0), o1 = bfhi(w0), o2 = bflo(w1), o3 = bfhi(w1);
;                 const float y0 = nv[k][0] * rs * gv[k][0] * __builtin_amdgcn_rcpf(1.f + __expf(-o0)), y1 = nv[k][1] * rs * gv[k][1] * __builtin_amdgcn_rcpf(1.f + __expf(-o1));
;                 const float y2 = nv[k][2] * rs * gv[k][2] * __builtin_amdgcn_rcpf(1.f + __expf(-o2)), y3 = nv[k][3] * rs * gv[k][3] * __builtin_amdgcn_rcpf(1.f + __expf(-o3));
;                 yo[k >> 1][2 * (k & 1)] = pk2(y0, y1); yo[k >> 1][2 * (k & 1) + 1] = pk2(y2, y3);
;             }
;             GAS char* yp = (GAS char*)Y + (size_t)(rowb + t0) * (DM * 2) + (size_t)vo_y;
;             *(GAS u32x4*)yp = yo[0]; *(GAS u32x4*)(yp + 16) = yo[1];
;         }
;         mstate = bL + M63;
;         if (c + 1 < 32) {
;             const float mi = bf2f(gmi) + ib, mf = bf2f(gmf) + fb; const float lf = fminf(mf, 0.f) - __logf(1.f + __expf(-fabsf(mf)));
;             bc = scan_add(lf, lane); av = mi - bc; pm = scan_max(av, lane); }
	v_add_f32_e32 v88, v88, v89
	v_fmamk_f32 v88, v88, 0x3c000000, v138
	v_mul_f32_e32 v89, 0x4b800000, v88
	v_cmp_gt_f32_e32 vcc, s76, v88
	s_nop 1
	v_cndmask_b32_e32 v88, v88, v89, vcc
	v_rsq_f32_e32 v108, v88
	ds_read_b128 v[88:91], v109 offset:16
	ds_read_b128 v[92:95], v109 offset:32
	ds_read_b128 v[96:99], v109 offset:48
	v_mul_f32_e32 v109, 0x45800000, v108
	v_cndmask_b32_e32 v108, v108, v109, vcc
	v_lshlrev_b32_e32 v109, 16, v84
	v_mul_f32_e32 v109, 0xbfb8aa3b, v109
	v_exp_f32_e32 v109, v109
	v_and_b32_e32 v84, 0xffff0000, v84
	v_mul_f32_e32 v84, 0xbfb8aa3b, v84
	v_exp_f32_e32 v123, v84
	v_add_f32_e32 v84, 1.0, v109
	v_pk_mul_f32 v[110:111], v[110:111], v[108:109] op_sel_hi:[1,0]
	v_mul_f32_e32 v109, 0xbfb8aa3b, v122
	v_exp_f32_e32 v109, v109
	v_mul_f32_e32 v122, 0xbfb8aa3b, v124
	v_exp_f32_e32 v122, v122
	v_add_f32_e32 v85, 1.0, v123
	v_rcp_f32_e32 v84, v84
	v_rcp_f32_e32 v85, v85
	v_add_f32_e32 v109, 1.0, v109
	v_pk_mul_f32 v[104:105], v[104:105], v[110:111]
	v_rcp_f32_e32 v110, v109
	v_add_f32_e32 v109, 1.0, v122
	v_rcp_f32_e32 v111, v109
	v_pk_mul_f32 v[84:85], v[84:85], v[104:105]
	v_pk_mul_f32 v[104:105], v[112:113], v[108:109] op_sel_hi:[1,0]
	v_cvt_pk_bf16_f32 v84, v84, v85
	v_pk_mul_f32 v[104:105], v[106:107], v[104:105]
	v_lshlrev_b32_e32 v106, 16, v87
	v_pk_mul_f32 v[104:105], v[110:111], v[104:105]
	v_and_b32_e32 v107, 0xffff0000, v87
	v_cvt_pk_bf16_f32 v85, v104, v105
	v_lshlrev_b32_e32 v104, 16, v86
	v_and_b32_e32 v86, 0xffff0000, v86
	v_mul_f32_e32 v104, 0xbfb8aa3b, v104
	v_mul_f32_e32 v86, 0xbfb8aa3b, v86
	v_exp_f32_e32 v104, v104
	v_exp_f32_e32 v105, v86
	v_mul_f32_e32 v106, 0xbfb8aa3b, v106
	v_mul_f32_e32 v107, 0xbfb8aa3b, v107
	v_exp_f32_e32 v106, v106
	v_exp_f32_e32 v107, v107
	v_add_f32_e32 v86, 1.0, v104
	v_add_f32_e32 v87, 1.0, v105
	v_rcp_f32_e32 v86, v86
	v_rcp_f32_e32 v87, v87
	v_pk_mul_f32 v[104:105], v[114:115], v[108:109] op_sel_hi:[1,0]
	s_andn2_b64 vcc, exec, s[2:3]
	s_waitcnt lgkmcnt(2)
	v_pk_mul_f32 v[88:89], v[88:89], v[104:105]
	v_add_f32_e32 v104, 1.0, v106
	v_add_f32_e32 v105, 1.0, v107
	v_rcp_f32_e32 v104, v104
	v_rcp_f32_e32 v105, v105
	v_pk_mul_f32 v[86:87], v[86:87], v[88:89]
	v_pk_mul_f32 v[88:89], v[116:117], v[108:109] op_sel_hi:[1,0]
	v_cvt_pk_bf16_f32 v86, v86, v87
	v_pk_mul_f32 v[88:89], v[90:91], v[88:89]
	v_lshlrev_b32_e32 v90, 16, v81
	v_pk_mul_f32 v[88:89], v[104:105], v[88:89]
	v_and_b32_e32 v91, 0xffff0000, v81
	v_cvt_pk_bf16_f32 v87, v88, v89
	v_lshlrev_b32_e32 v88, 16, v80
	v_and_b32_e32 v80, 0xffff0000, v80
	v_mul_f32_e32 v88, 0xbfb8aa3b, v88
	v_mul_f32_e32 v80, 0xbfb8aa3b, v80
	v_exp_f32_e32 v88, v88
	v_exp_f32_e32 v89, v80
	v_mul_f32_e32 v90, 0xbfb8aa3b, v90
	v_mul_f32_e32 v91, 0xbfb8aa3b, v91
	v_exp_f32_e32 v90, v90
	v_exp_f32_e32 v91, v91
	v_add_f32_e32 v80, 1.0, v88
	v_add_f32_e32 v81, 1.0, v89
	v_rcp_f32_e32 v80, v80
	v_rcp_f32_e32 v81, v81
	v_add_f32_e32 v90, 1.0, v90
	v_add_f32_e32 v91, 1.0, v91
	v_pk_mul_f32 v[88:89], v[120:121], v[108:109] op_sel_hi:[1,0]
	v_rcp_f32_e32 v90, v90
	v_rcp_f32_e32 v91, v91
	s_waitcnt lgkmcnt(1)
	v_pk_mul_f32 v[88:89], v[92:93], v[88:89]
	global_store_dwordx4 v[126:127], v[84:87], off offset:-16
	v_pk_mul_f32 v[80:81], v[80:81], v[88:89]
	v_pk_mul_f32 v[88:89], v[118:119], v[108:109] op_sel_hi:[1,0]
	v_cvt_pk_bf16_f32 v80, v80, v81
	v_pk_mul_f32 v[88:89], v[94:95], v[88:89]
	s_nop 0
	v_pk_mul_f32 v[88:89], v[90:91], v[88:89]
	v_lshlrev_b32_e32 v90, 16, v83
	v_cvt_pk_bf16_f32 v81, v88, v89
	v_lshlrev_b32_e32 v88, 16, v82
	v_and_b32_e32 v82, 0xffff0000, v82
	v_mul_f32_e32 v88, 0xbfb8aa3b, v88
	v_mul_f32_e32 v82, 0xbfb8aa3b, v82
	v_exp_f32_e32 v88, v88
	v_exp_f32_e32 v89, v82
	v_and_b32_e32 v91, 0xffff0000, v83
	v_mul_f32_e32 v90, 0xbfb8aa3b, v90
	v_mul_f32_e32 v91, 0xbfb8aa3b, v91
	v_exp_f32_e32 v90, v90
	v_exp_f32_e32 v91, v91
	v_add_f32_e32 v82, 1.0, v88
	v_add_f32_e32 v83, 1.0, v89
	v_rcp_f32_e32 v82, v82
	v_rcp_f32_e32 v83, v83
	v_add_f32_e32 v90, 1.0, v90
	v_add_f32_e32 v91, 1.0, v91
	v_pk_mul_f32 v[88:89], v[100:101], v[108:109] op_sel_hi:[1,0]
	v_rcp_f32_e32 v90, v90
	v_rcp_f32_e32 v91, v91
	s_waitcnt lgkmcnt(0)
	v_pk_mul_f32 v[88:89], v[96:97], v[88:89]
	s_nop 0
	v_pk_mul_f32 v[82:83], v[82:83], v[88:89]
	v_pk_mul_f32 v[88:89], v[102:103], v[108:109] op_sel_hi:[1,0]
	v_cvt_pk_bf16_f32 v82, v82, v83
	v_pk_mul_f32 v[88:89], v[98:99], v[88:89]
	s_nop 0
	v_pk_mul_f32 v[88:89], v[90:91], v[88:89]
	s_nop 0
	v_cvt_pk_bf16_f32 v83, v88, v89
	global_store_dwordx4 v[126:127], v[80:83], off
	s_cbranch_vccnz .LBB0_1024
	s_nop 0
	v_lshlrev_b32_e32 v80, 16, v148
	v_add_f32_e32 v80, v145, v80
	v_mul_f32_e64 v81, |v80|, s75
	v_exp_f32_e32 v81, v81
	v_min_f32_e32 v80, 0, v80
	v_cmp_gt_i32_e64 s[10:11], 2, v167
	v_cmp_gt_i32_e64 s[12:13], 4, v167
	v_add_f32_e32 v81, 1.0, v81
	v_cmp_gt_f32_e32 vcc, s76, v81
	v_cmp_gt_i32_e64 s[14:15], 8, v167
	v_cmp_gt_i32_e64 s[16:17], 16, v167
	v_cndmask_b32_e64 v82, 0, 32, vcc
	v_ldexp_f32 v81, v81, v82
	v_log_f32_e32 v81, v81
	v_cndmask_b32_e32 v82, 0, v142, vcc
	v_cmp_gt_i32_e64 s[18:19], 32, v167
	v_mul_f32_e32 v83, 0x3f317217, v81
	v_fma_f32 v83, v81, s77, -v83
	v_fmac_f32_e32 v83, 0x3377d1cf, v81
	v_fmac_f32_e32 v83, 0x3f317217, v81
	v_cmp_lt_f32_e64 vcc, |v81|, s78
	s_nop 1
	v_cndmask_b32_e32 v81, v81, v83, vcc
	v_sub_f32_e32 v81, v81, v82
	v_sub_f32_e32 v80, v80, v81
	v_lshlrev_b32_e32 v82, 16, v147
	v_add_f32_e32 v82, v144, v82
	v_mov_b32_e32 v155, v80
	s_nop 1
	v_add_f32_dpp v155, v155, v155 row_shr:1 row_mask:0xf bank_mask:0xf
	s_nop 1
	v_add_f32_dpp v155, v155, v155 row_shr:2 row_mask:0xf bank_mask:0xf
	s_nop 1
	v_add_f32_dpp v155, v155, v155 row_shr:4 row_mask:0xf bank_mask:0xf
	s_nop 1
	v_add_f32_dpp v155, v155, v155 row_shr:8 row_mask:0xf bank_mask:0xf
	s_nop 1
	v_add_f32_dpp v155, v155, v155 row_bcast:15 row_mask:0xa bank_mask:0xf
	s_nop 1
	v_add_f32_dpp v155, v155, v155 row_bcast:31 row_mask:0xc bank_mask:0xf
	v_sub_f32_e32 v156, v82, v155
	v_mov_b32_e32 v157, v156
	s_nop 1
	v_max_f32_dpp v157, v157, v157 row_shr:1 row_mask:0xf bank_mask:0xf
	s_nop 1
	v_max_f32_dpp v157, v157, v157 row_shr:2 row_mask:0xf bank_mask:0xf
	s_nop 1
	v_max_f32_dpp v157, v157, v157 row_shr:4 row_mask:0xf bank_mask:0xf
	s_nop 1
	v_max_f32_dpp v157, v157, v157 row_shr:8 row_mask:0xf bank_mask:0xf
	s_nop 1
	v_max_f32_dpp v157, v157, v157 row_bcast:15 row_mask:0xa bank_mask:0xf
	s_nop 1
	v_max_f32_dpp v157, v157, v157 row_bcast:31 row_mask:0xc bank_mask:0xf
	s_branch .LBB0_1024
